# down GEMM epilogue applies the residual update in place (XB += g1*Y + g2*acc, f32 acc) for layers 1-2; norm1 of layers 2-3 reads XB only
# baseline (speedup 1.0000x reference)
; __device__ __forceinline__ void norm_mod_phase(Frame& F, int L, const float* gvec, int sh_chunk, int nrows, const float* pg, const float* pg2, const float* xlat, const float* xctx) {
;     ...
;         const bool lat = r < MLAT, xbf = lat ? (xlat == nullptr) : (xctx == nullptr);
;         const bool h1 = pg != nullptr && lat, h2 = pg2 != nullptr && lat, hc = pg != nullptr && !lat;
;         u32x4 xraw[8]; u32x2 aux[4][8];
;         if (xbf) { const u32x2* xb = (const u32x2*)((const bf16_t*)(F.ws + (lat ? WS_XB : WS_XC)) + (size_t)(lat ? r : r - MLAT) * D) + lane;
; #pragma unroll
;             for (int j = 0; j < 8; ++j) { const u32x2 w = __builtin_nontemporal_load(xb + 64 * j); xraw[j].x = w.x; xraw[j].y = w.y; }
;         } else { const u32x4* xr = (const u32x4*)(lat ? xlat + (size_t)r * D : xctx + (size_t)(r - MLAT) * D) + lane;
; #pragma unroll
;             for (int j = 0; j < 8; ++j) xraw[j] = __builtin_nontemporal_load(xr + 64 * j); }
;         if (h1) { const u32x2* yp = (const u32x2*)((const bf16_t*)(F.ws + WS_Y) + (size_t)r * D) + lane;
; #pragma unroll
;             for (int j = 0; j < 8; ++j) aux[0][j] = __builtin_nontemporal_load(yp + 64 * j); }
.LBB0_215:
	s_and_b64 s[4:5], s[0:1], s[28:29]
	s_cmp_lt_u32 s82, 2
	s_cselect_b64 s[100:101], -1, 0
	s_and_b64 s[4:5], s[4:5], s[100:101]
	v_cndmask_b32_e64 v32, 0, 1, s[4:5]
	v_cmp_ne_u32_e64 s[40:41], 1, v32
	s_andn2_b64 vcc, exec, s[4:5]
	s_cbranch_vccnz .LBB0_217
	s_ashr_i32 s11, s10, 31
	s_lshl_b64 s[4:5], s[10:11], 12
	v_lshl_add_u64 v[32:33], v[68:69], 0, s[4:5]
	global_load_dwordx2 v[116:117], v[32:33], off nt
	global_load_dwordx2 v[118:119], v[32:33], off offset:512 nt
	global_load_dwordx2 v[120:121], v[32:33], off offset:1024 nt
	global_load_dwordx2 v[122:123], v[32:33], off offset:1536 nt
	global_load_dwordx2 v[124:125], v[32:33], off offset:2048 nt
	global_load_dwordx2 v[126:127], v[32:33], off offset:2560 nt
	global_load_dwordx2 v[128:129], v[32:33], off offset:3072 nt
	global_load_dwordx2 v[132:133], v[32:33], off offset:3584 nt

; #define LAS __attribute__((address_space(3)))
; __device__ __forceinline__ unsigned cvt_pk_bf16(float lo, float hi) { const f32x2 v = {lo, hi}; return __builtin_bit_cast(unsigned, __builtin_convertvector(v, bf16x2_t)); }
; __device__ __forceinline__ float bf_lo(unsigned u) { return __uint_as_float(u << 16); }
; __device__ __forceinline__ float bf_hi(unsigned u) { return __uint_as_float(u & 0xffff0000u); }
;     template <class Sched> __device__ __forceinline__ void operator()(const f32x4 (&acc)[2][2][4][2], const Unit& u, const Sched& S, int wr, int wc, int fr, int fq) const {
;         const int rl0 = wr * 64 + fr, cl0 = wc * 32 + 8 * fq;
;         char* uo; int ldo, kind; S.out(u, uo, ldo, kind);
;         asm volatile("" : "+s"(ldo));
;         if (kind == 0) {
;             bf16_t* base = (bf16_t*)uo;
; #pragma unroll
;             for (int ai = 0; ai < 2; ++ai)
; #pragma unroll
;                 for (int m = 0; m < 4; ++m) { bf16_t* rowp = base + (size_t)(rl0 + ai * HALF + m * 16) * ldo + cl0;
; #pragma unroll
;                     for (int bj = 0; bj < 2; ++bj) { const f32x4 v0 = acc[ai][bj][m][0], v1 = acc[ai][bj][m][1];
;                         u32x4 w; w.x = cvt_pk_bf16(v0[0], v0[1]); w.y = cvt_pk_bf16(v0[2], v0[3]); w.z = cvt_pk_bf16(v1[0], v1[1]); w.w = cvt_pk_bf16(v1[2], v1[3]);
;                         *(u32x4*)(rowp + bj * HALF) = w; } }
; __device__ __forceinline__ void norm_mod_phase(Frame& F, int L, const float* gvec, int sh_chunk, int nrows, const float* pg, const float* pg2, const float* xlat, const float* xctx) {
;     ...
;         if (h2) {
;             const LAS f32x4* gq = vq + 3 * (D / 4); u32x2* xw_ = (u32x2*)((bf16_t*)(F.ws + WS_XB) + (size_t)r * D) + lane;
; #pragma unroll
;             for (int j = 0; j < 8; ++j) { const u32x2 yy = aux[1][j]; const f32x4 y4 = {bf_lo(yy.x), bf_hi(yy.x), bf_lo(yy.y), bf_hi(yy.y)}; v[j] += gq[64 * j] * y4; u32x2 w; w.x = cvt_pk_bf16(v[j].x, v[j].y); w.y = cvt_pk_bf16(v[j].z, v[j].w); xw_[64 * j] = w; }
;         }
.LBB0_1344:
	s_andn2_b64 vcc, exec, s[46:47]
	s_cbranch_vccnz .LBB0_1326
	s_sub_u32 s100, s82, 1
	s_cmp_lt_u32 s100, 2
	s_cbranch_scc1 .Ldown_res_epi
	s_ashr_i32 s31, s30, 31
	s_ashr_i32 s35, s34, 31
	s_lshl_b64 s[4:5], s[34:35], 9
	s_lshl_b64 s[30:31], s[30:31], 20
	v_readlane_b32 s34, v251, 26
	v_readlane_b32 s35, v251, 27
	s_add_u32 s17, s34, s30
	s_addc_u32 s27, s35, s31
	s_add_u32 s4, s17, s4
	s_addc_u32 s5, s27, s5
	s_branch .LBB0_1326
.Ldown_res_epi:
	s_lshl_b32 s4, s30, 20
	s_lshl_b32 s5, s34, 9
	s_add_u32 s4, s4, s5
	s_add_u32 s4, s4, 0x4f300000
	s_add_u32 s4, s66, s4
	s_addc_u32 s5, s67, 0
	s_lshr_b32 s17, s30, 3
	s_mul_i32 s27, s82, 9
	s_add_i32 s17, s17, s27
	s_mul_i32 s17, s17, 0xc000
	s_lshl_b32 s27, s34, 10
	s_add_i32 s17, s17, s27
	s_add_i32 s17, s17, 0x104000
	s_add_u32 s30, s66, s17
	s_addc_u32 s31, s67, 0
	v_lshl_add_u64 v[162:163], v[136:137], 2, s[30:31]
	s_add_u32 s30, s30, 0x6000
	s_addc_u32 s31, s31, 0
	global_load_dwordx4 v[178:181], v[162:163], off
	global_load_dwordx4 v[182:185], v[162:163], off offset:16
	global_load_dwordx4 v[186:189], v[162:163], off offset:512
	global_load_dwordx4 v[190:193], v[162:163], off offset:528
	v_lshl_add_u64 v[164:165], v[136:137], 2, s[30:31]
	global_load_dwordx4 v[194:197], v[164:165], off
	global_load_dwordx4 v[198:201], v[164:165], off offset:16
	global_load_dwordx4 v[202:205], v[164:165], off offset:512
	global_load_dwordx4 v[206:209], v[164:165], off offset:528
	v_lshl_add_u64 v[156:157], v[136:137], 1, s[4:5]
	s_mov_b32 s100, 0xf7000000
	s_mov_b32 s101, -1
	s_movk_i32 s17, 0x800
	v_mad_i64_i32 v[162:163], vcc, s17, v134, 0
	v_lshl_add_u64 v[158:159], v[162:163], 1, v[156:157]
	v_lshl_add_u64 v[164:165], v[158:159], 0, s[100:101]
	global_load_dwordx4 v[210:213], v[158:159], off
	global_load_dwordx4 v[214:217], v[158:159], off offset:256
	global_load_dwordx4 v[218:221], v[164:165], off
	global_load_dwordx4 v[222:225], v[164:165], off offset:256
	v_mad_i64_i32 v[162:163], vcc, s17, v138, 0
	v_lshl_add_u64 v[160:161], v[162:163], 1, v[156:157]
	v_lshl_add_u64 v[164:165], v[160:161], 0, s[100:101]
	global_load_dwordx4 v[226:229], v[160:161], off
	global_load_dwordx4 v[230:233], v[160:161], off offset:256
	global_load_dwordx4 v[234:237], v[164:165], off
	global_load_dwordx4 v[246:249], v[164:165], off offset:256
	s_waitcnt vmcnt(4)
	v_lshlrev_b32_e32 v164, 16, v210
	v_and_b32_e32 v165, 0xffff0000, v210
	v_lshlrev_b32_e32 v166, 16, v218
	v_and_b32_e32 v167, 0xffff0000, v218
	v_lshlrev_b32_e32 v168, 16, v211
	v_and_b32_e32 v169, 0xffff0000, v211
	v_lshlrev_b32_e32 v170, 16, v219
	v_and_b32_e32 v171, 0xffff0000, v219
	v_pk_fma_f32 v[164:165], v[178:179], v[166:167], v[164:165]
	v_pk_fma_f32 v[168:169], v[180:181], v[170:171], v[168:169]
	v_pk_fma_f32 v[124:125], v[194:195], v[124:125], v[164:165]
	v_pk_fma_f32 v[126:127], v[196:197], v[126:127], v[168:169]
	v_lshlrev_b32_e32 v164, 16, v212
	v_and_b32_e32 v165, 0xffff0000, v212
	v_lshlrev_b32_e32 v166, 16, v220
	v_and_b32_e32 v167, 0xffff0000, v220
	v_lshlrev_b32_e32 v168, 16, v213
	v_and_b32_e32 v169, 0xffff0000, v213
	v_lshlrev_b32_e32 v170, 16, v221
	v_and_b32_e32 v171, 0xffff0000, v221
	v_pk_fma_f32 v[164:165], v[182:183], v[166:167], v[164:165]
	v_pk_fma_f32 v[168:169], v[184:185], v[170:171], v[168:169]
	v_pk_fma_f32 v[120:121], v[198:199], v[120:121], v[164:165]
	v_pk_fma_f32 v[122:123], v[200:201], v[122:123], v[168:169]
	s_nop 0
	v_cvt_pk_bf16_f32 v172, v124, v125
	v_cvt_pk_bf16_f32 v173, v126, v127
	v_cvt_pk_bf16_f32 v174, v120, v121
	v_cvt_pk_bf16_f32 v175, v122, v123
	global_store_dwordx4 v[158:159], v[172:175], off
	v_lshlrev_b32_e32 v164, 16, v214
	v_and_b32_e32 v165, 0xffff0000, v214
	v_lshlrev_b32_e32 v166, 16, v222
	v_and_b32_e32 v167, 0xffff0000, v222
	v_lshlrev_b32_e32 v168, 16, v215
	v_and_b32_e32 v169, 0xffff0000, v215
	v_lshlrev_b32_e32 v170, 16, v223
	v_and_b32_e32 v171, 0xffff0000, v223
	v_pk_fma_f32 v[164:165], v[186:187], v[166:167], v[164:165]
	v_pk_fma_f32 v[168:169], v[188:189], v[170:171], v[168:169]
	v_pk_fma_f32 v[108:109], v[202:203], v[108:109], v[164:165]
	v_pk_fma_f32 v[110:111], v[204:205], v[110:111], v[168:169]
	v_lshlrev_b32_e32 v164, 16, v216
	v_and_b32_e32 v165, 0xffff0000, v216
	v_lshlrev_b32_e32 v166, 16, v224
	v_and_b32_e32 v167, 0xffff0000, v224
	v_lshlrev_b32_e32 v168, 16, v217
	v_and_b32_e32 v169, 0xffff0000, v217
	v_lshlrev_b32_e32 v170, 16, v225
	v_and_b32_e32 v171, 0xffff0000, v225
	v_pk_fma_f32 v[164:165], v[190:191], v[166:167], v[164:165]
	v_pk_fma_f32 v[168:169], v[192:193], v[170:171], v[168:169]
	v_pk_fma_f32 v[104:105], v[206:207], v[104:105], v[164:165]
	v_pk_fma_f32 v[106:107], v[208:209], v[106:107], v[168:169]
	s_nop 0
	v_cvt_pk_bf16_f32 v172, v108, v109
	v_cvt_pk_bf16_f32 v173, v110, v111
	v_cvt_pk_bf16_f32 v174, v104, v105
	v_cvt_pk_bf16_f32 v175, v106, v107
	global_store_dwordx4 v[158:159], v[172:175], off offset:256
	v_mad_i64_i32 v[162:163], vcc, s17, v140, 0
	v_lshl_add_u64 v[158:159], v[162:163], 1, v[156:157]
	v_lshl_add_u64 v[164:165], v[158:159], 0, s[100:101]
	global_load_dwordx4 v[210:213], v[158:159], off
	global_load_dwordx4 v[214:217], v[158:159], off offset:256
	global_load_dwordx4 v[218:221], v[164:165], off
	global_load_dwordx4 v[222:225], v[164:165], off offset:256
	s_waitcnt vmcnt(6)
; #define LAS __attribute__((address_space(3)))
; __device__ __forceinline__ unsigned cvt_pk_bf16(float lo, float hi) { const f32x2 v = {lo, hi}; return __builtin_bit_cast(unsigned, __builtin_convertvector(v, bf16x2_t)); }
; __device__ __forceinline__ float bf_lo(unsigned u) { return __uint_as_float(u << 16); }
; __device__ __forceinline__ float bf_hi(unsigned u) { return __uint_as_float(u & 0xffff0000u); }
;     template <class Sched> __device__ __forceinline__ void operator()(const f32x4 (&acc)[2][2][4][2], const Unit& u, const Sched& S, int wr, int wc, int fr, int fq) const {
;     ...
;                 for (int m = 0; m < 4; ++m) { bf16_t* rowp = base + (size_t)(rl0 + ai * HALF + m * 16) * ldo + cl0;
; #pragma unroll
;                     for (int bj = 0; bj < 2; ++bj) { const f32x4 v0 = acc[ai][bj][m][0], v1 = acc[ai][bj][m][1];
;                         u32x4 w; w.x = cvt_pk_bf16(v0[0], v0[1]); w.y = cvt_pk_bf16(v0[2], v0[3]); w.z = cvt_pk_bf16(v1[0], v1[1]); w.w = cvt_pk_bf16(v1[2], v1[3]);
;                         *(u32x4*)(rowp + bj * HALF) = w; } }
; __device__ __forceinline__ void norm_mod_phase(Frame& F, int L, const float* gvec, int sh_chunk, int nrows, const float* pg, const float* pg2, const float* xlat, const float* xctx) {
;     ...
;         if (h2) {
;             const LAS f32x4* gq = vq + 3 * (D / 4); u32x2* xw_ = (u32x2*)((bf16_t*)(F.ws + WS_XB) + (size_t)r * D) + lane;
; #pragma unroll
;             for (int j = 0; j < 8; ++j) { const u32x2 yy = aux[1][j]; const f32x4 y4 = {bf_lo(yy.x), bf_hi(yy.x), bf_lo(yy.y), bf_hi(yy.y)}; v[j] += gq[64 * j] * y4; u32x2 w; w.x = cvt_pk_bf16(v[j].x, v[j].y); w.y = cvt_pk_bf16(v[j].z, v[j].w); xw_[64 * j] = w; }
;         }
	v_lshlrev_b32_e32 v164, 16, v226
	v_and_b32_e32 v165, 0xffff0000, v226
	v_lshlrev_b32_e32 v166, 16, v234
	v_and_b32_e32 v167, 0xffff0000, v234
	v_lshlrev_b32_e32 v168, 16, v227
	v_and_b32_e32 v169, 0xffff0000, v227
	v_lshlrev_b32_e32 v170, 16, v235
	v_and_b32_e32 v171, 0xffff0000, v235
	v_pk_fma_f32 v[164:165], v[178:179], v[166:167], v[164:165]
	v_pk_fma_f32 v[168:169], v[180:181], v[170:171], v[168:169]
	v_pk_fma_f32 v[116:117], v[194:195], v[116:117], v[164:165]
	v_pk_fma_f32 v[118:119], v[196:197], v[118:119], v[168:169]
	v_lshlrev_b32_e32 v164, 16, v228
	v_and_b32_e32 v165, 0xffff0000, v228
	v_lshlrev_b32_e32 v166, 16, v236
	v_and_b32_e32 v167, 0xffff0000, v236
	v_lshlrev_b32_e32 v168, 16, v229
	v_and_b32_e32 v169, 0xffff0000, v229
	v_lshlrev_b32_e32 v170, 16, v237
	v_and_b32_e32 v171, 0xffff0000, v237
	v_pk_fma_f32 v[164:165], v[182:183], v[166:167], v[164:165]
	v_pk_fma_f32 v[168:169], v[184:185], v[170:171], v[168:169]
	v_pk_fma_f32 v[112:113], v[198:199], v[112:113], v[164:165]
	v_pk_fma_f32 v[114:115], v[200:201], v[114:115], v[168:169]
	s_nop 0
	v_cvt_pk_bf16_f32 v172, v116, v117
	v_cvt_pk_bf16_f32 v173, v118, v119
	v_cvt_pk_bf16_f32 v174, v112, v113
	v_cvt_pk_bf16_f32 v175, v114, v115
	global_store_dwordx4 v[160:161], v[172:175], off
	v_lshlrev_b32_e32 v164, 16, v230
	v_and_b32_e32 v165, 0xffff0000, v230
	v_lshlrev_b32_e32 v166, 16, v246
	v_and_b32_e32 v167, 0xffff0000, v246
	v_lshlrev_b32_e32 v168, 16, v231
	v_and_b32_e32 v169, 0xffff0000, v231
	v_lshlrev_b32_e32 v170, 16, v247
	v_and_b32_e32 v171, 0xffff0000, v247
	v_pk_fma_f32 v[164:165], v[186:187], v[166:167], v[164:165]
	v_pk_fma_f32 v[168:169], v[188:189], v[170:171], v[168:169]
	v_pk_fma_f32 v[92:93], v[202:203], v[92:93], v[164:165]
	v_pk_fma_f32 v[94:95], v[204:205], v[94:95], v[168:169]
	v_lshlrev_b32_e32 v164, 16, v232
	v_and_b32_e32 v165, 0xffff0000, v232
	v_lshlrev_b32_e32 v166, 16, v248
	v_and_b32_e32 v167, 0xffff0000, v248
	v_lshlrev_b32_e32 v168, 16, v233
	v_and_b32_e32 v169, 0xffff0000, v233
	v_lshlrev_b32_e32 v170, 16, v249
	v_and_b32_e32 v171, 0xffff0000, v249
	v_pk_fma_f32 v[164:165], v[190:191], v[166:167], v[164:165]
	v_pk_fma_f32 v[168:169], v[192:193], v[170:171], v[168:169]
	v_pk_fma_f32 v[88:89], v[206:207], v[88:89], v[164:165]
	v_pk_fma_f32 v[90:91], v[208:209], v[90:91], v[168:169]
	s_nop 0
	v_cvt_pk_bf16_f32 v172, v92, v93
	v_cvt_pk_bf16_f32 v173, v94, v95
	v_cvt_pk_bf16_f32 v174, v88, v89
	v_cvt_pk_bf16_f32 v175, v90, v91
	global_store_dwordx4 v[160:161], v[172:175], off offset:256
	v_mad_i64_i32 v[162:163], vcc, s17, v142, 0
	v_lshl_add_u64 v[160:161], v[162:163], 1, v[156:157]
	v_lshl_add_u64 v[164:165], v[160:161], 0, s[100:101]
	global_load_dwordx4 v[226:229], v[160:161], off
	global_load_dwordx4 v[230:233], v[160:161], off offset:256
	global_load_dwordx4 v[234:237], v[164:165], off
	global_load_dwordx4 v[246:249], v[164:165], off offset:256
	s_waitcnt vmcnt(6)
	v_lshlrev_b32_e32 v164, 16, v210
	v_and_b32_e32 v165, 0xffff0000, v210
	v_lshlrev_b32_e32 v166, 16, v218
	v_and_b32_e32 v167, 0xffff0000, v218
	v_lshlrev_b32_e32 v168, 16, v211
	v_and_b32_e32 v169, 0xffff0000, v211
	v_lshlrev_b32_e32 v170, 16, v219
	v_and_b32_e32 v171, 0xffff0000, v219
	v_pk_fma_f32 v[164:165], v[178:179], v[166:167], v[164:165]
	v_pk_fma_f32 v[168:169], v[180:181], v[170:171], v[168:169]
	v_pk_fma_f32 v[100:101], v[194:195], v[100:101], v[164:165]
	v_pk_fma_f32 v[102:103], v[196:197], v[102:103], v[168:169]
	v_lshlrev_b32_e32 v164, 16, v212
	v_and_b32_e32 v165, 0xffff0000, v212
	v_lshlrev_b32_e32 v166, 16, v220
	v_and_b32_e32 v167, 0xffff0000, v220
	v_lshlrev_b32_e32 v168, 16, v213
	v_and_b32_e32 v169, 0xffff0000, v213
	v_lshlrev_b32_e32 v170, 16, v221
	v_and_b32_e32 v171, 0xffff0000, v221
	v_pk_fma_f32 v[164:165], v[182:183], v[166:167], v[164:165]
	v_pk_fma_f32 v[168:169], v[184:185], v[170:171], v[168:169]
	v_pk_fma_f32 v[96:97], v[198:199], v[96:97], v[164:165]
	v_pk_fma_f32 v[98:99], v[200:201], v[98:99], v[168:169]
	s_nop 0
	v_cvt_pk_bf16_f32 v172, v100, v101
	v_cvt_pk_bf16_f32 v173, v102, v103
	v_cvt_pk_bf16_f32 v174, v96, v97
	v_cvt_pk_bf16_f32 v175, v98, v99
	global_store_dwordx4 v[158:159], v[172:175], off
	v_lshlrev_b32_e32 v164, 16, v214
	v_and_b32_e32 v165, 0xffff0000, v214
	v_lshlrev_b32_e32 v166, 16, v222
	v_and_b32_e32 v167, 0xffff0000, v222
	v_lshlrev_b32_e32 v168, 16, v215
	v_and_b32_e32 v169, 0xffff0000, v215
	v_lshlrev_b32_e32 v170, 16, v223
	v_and_b32_e32 v171, 0xffff0000, v223
	v_pk_fma_f32 v[164:165], v[186:187], v[166:167], v[164:165]
	v_pk_fma_f32 v[168:169], v[188:189], v[170:171], v[168:169]
	v_pk_fma_f32 v[76:77], v[202:203], v[76:77], v[164:165]
	v_pk_fma_f32 v[78:79], v[204:205], v[78:79], v[168:169]
	v_lshlrev_b32_e32 v164, 16, v216
	v_and_b32_e32 v165, 0xffff0000, v216
	v_lshlrev_b32_e32 v166, 16, v224
	v_and_b32_e32 v167, 0xffff0000, v224
	v_lshlrev_b32_e32 v168, 16, v217
	v_and_b32_e32 v169, 0xffff0000, v217
	v_lshlrev_b32_e32 v170, 16, v225
	v_and_b32_e32 v171, 0xffff0000, v225
	v_pk_fma_f32 v[164:165], v[190:191], v[166:167], v[164:165]
	v_pk_fma_f32 v[168:169], v[192:193], v[170:171], v[168:169]
	v_pk_fma_f32 v[72:73], v[206:207], v[72:73], v[164:165]
	v_pk_fma_f32 v[74:75], v[208:209], v[74:75], v[168:169]
	s_nop 0
	v_cvt_pk_bf16_f32 v172, v76, v77
	v_cvt_pk_bf16_f32 v173, v78, v79
	v_cvt_pk_bf16_f32 v174, v72, v73
	v_cvt_pk_bf16_f32 v175, v74, v75
	global_store_dwordx4 v[158:159], v[172:175], off offset:256
	v_mad_i64_i32 v[162:163], vcc, s17, v144, 0
	v_lshl_add_u64 v[158:159], v[162:163], 1, v[156:157]
	v_lshl_add_u64 v[164:165], v[158:159], 0, s[100:101]
	global_load_dwordx4 v[210:213], v[158:159], off
	global_load_dwordx4 v[214:217], v[158:159], off offset:256
	global_load_dwordx4 v[218:221], v[164:165], off
	global_load_dwordx4 v[222:225], v[164:165], off offset:256
	s_waitcnt vmcnt(6)
; #define LAS __attribute__((address_space(3)))
; __device__ __forceinline__ unsigned cvt_pk_bf16(float lo, float hi) { const f32x2 v = {lo, hi}; return __builtin_bit_cast(unsigned, __builtin_convertvector(v, bf16x2_t)); }
; __device__ __forceinline__ float bf_lo(unsigned u) { return __uint_as_float(u << 16); }
; __device__ __forceinline__ float bf_hi(unsigned u) { return __uint_as_float(u & 0xffff0000u); }
;     template <class Sched> __device__ __forceinline__ void operator()(const f32x4 (&acc)[2][2][4][2], const Unit& u, const Sched& S, int wr, int wc, int fr, int fq) const {
;     ...
;                 for (int m = 0; m < 4; ++m) { bf16_t* rowp = base + (size_t)(rl0 + ai * HALF + m * 16) * ldo + cl0;
; #pragma unroll
;                     for (int bj = 0; bj < 2; ++bj) { const f32x4 v0 = acc[ai][bj][m][0], v1 = acc[ai][bj][m][1];
;                         u32x4 w; w.x = cvt_pk_bf16(v0[0], v0[1]); w.y = cvt_pk_bf16(v0[2], v0[3]); w.z = cvt_pk_bf16(v1[0], v1[1]); w.w = cvt_pk_bf16(v1[2], v1[3]);
;                         *(u32x4*)(rowp + bj * HALF) = w; } }
; __device__ __forceinline__ void norm_mod_phase(Frame& F, int L, const float* gvec, int sh_chunk, int nrows, const float* pg, const float* pg2, const float* xlat, const float* xctx) {
;     ...
;         if (h2) {
;             const LAS f32x4* gq = vq + 3 * (D / 4); u32x2* xw_ = (u32x2*)((bf16_t*)(F.ws + WS_XB) + (size_t)r * D) + lane;
; #pragma unroll
;             for (int j = 0; j < 8; ++j) { const u32x2 yy = aux[1][j]; const f32x4 y4 = {bf_lo(yy.x), bf_hi(yy.x), bf_lo(yy.y), bf_hi(yy.y)}; v[j] += gq[64 * j] * y4; u32x2 w; w.x = cvt_pk_bf16(v[j].x, v[j].y); w.y = cvt_pk_bf16(v[j].z, v[j].w); xw_[64 * j] = w; }
;         }
	v_lshlrev_b32_e32 v164, 16, v226
	v_and_b32_e32 v165, 0xffff0000, v226
	v_lshlrev_b32_e32 v166, 16, v234
	v_and_b32_e32 v167, 0xffff0000, v234
	v_lshlrev_b32_e32 v168, 16, v227
	v_and_b32_e32 v169, 0xffff0000, v227
	v_lshlrev_b32_e32 v170, 16, v235
	v_and_b32_e32 v171, 0xffff0000, v235
	v_pk_fma_f32 v[164:165], v[178:179], v[166:167], v[164:165]
	v_pk_fma_f32 v[168:169], v[180:181], v[170:171], v[168:169]
	v_pk_fma_f32 v[84:85], v[194:195], v[84:85], v[164:165]
	v_pk_fma_f32 v[86:87], v[196:197], v[86:87], v[168:169]
	v_lshlrev_b32_e32 v164, 16, v228
	v_and_b32_e32 v165, 0xffff0000, v228
	v_lshlrev_b32_e32 v166, 16, v236
	v_and_b32_e32 v167, 0xffff0000, v236
	v_lshlrev_b32_e32 v168, 16, v229
	v_and_b32_e32 v169, 0xffff0000, v229
	v_lshlrev_b32_e32 v170, 16, v237
	v_and_b32_e32 v171, 0xffff0000, v237
	v_pk_fma_f32 v[164:165], v[182:183], v[166:167], v[164:165]
	v_pk_fma_f32 v[168:169], v[184:185], v[170:171], v[168:169]
	v_pk_fma_f32 v[80:81], v[198:199], v[80:81], v[164:165]
	v_pk_fma_f32 v[82:83], v[200:201], v[82:83], v[168:169]
	s_nop 0
	v_cvt_pk_bf16_f32 v172, v84, v85
	v_cvt_pk_bf16_f32 v173, v86, v87
	v_cvt_pk_bf16_f32 v174, v80, v81
	v_cvt_pk_bf16_f32 v175, v82, v83
	global_store_dwordx4 v[160:161], v[172:175], off
	v_lshlrev_b32_e32 v164, 16, v230
	v_and_b32_e32 v165, 0xffff0000, v230
	v_lshlrev_b32_e32 v166, 16, v246
	v_and_b32_e32 v167, 0xffff0000, v246
	v_lshlrev_b32_e32 v168, 16, v231
	v_and_b32_e32 v169, 0xffff0000, v231
	v_lshlrev_b32_e32 v170, 16, v247
	v_and_b32_e32 v171, 0xffff0000, v247
	v_pk_fma_f32 v[164:165], v[186:187], v[166:167], v[164:165]
	v_pk_fma_f32 v[168:169], v[188:189], v[170:171], v[168:169]
	v_pk_fma_f32 v[68:69], v[202:203], v[68:69], v[164:165]
	v_pk_fma_f32 v[70:71], v[204:205], v[70:71], v[168:169]
	v_lshlrev_b32_e32 v164, 16, v232
	v_and_b32_e32 v165, 0xffff0000, v232
	v_lshlrev_b32_e32 v166, 16, v248
	v_and_b32_e32 v167, 0xffff0000, v248
	v_lshlrev_b32_e32 v168, 16, v233
	v_and_b32_e32 v169, 0xffff0000, v233
	v_lshlrev_b32_e32 v170, 16, v249
	v_and_b32_e32 v171, 0xffff0000, v249
	v_pk_fma_f32 v[164:165], v[190:191], v[166:167], v[164:165]
	v_pk_fma_f32 v[168:169], v[192:193], v[170:171], v[168:169]
	v_pk_fma_f32 v[64:65], v[206:207], v[64:65], v[164:165]
	v_pk_fma_f32 v[66:67], v[208:209], v[66:67], v[168:169]
	s_nop 0
	v_cvt_pk_bf16_f32 v172, v68, v69
	v_cvt_pk_bf16_f32 v173, v70, v71
	v_cvt_pk_bf16_f32 v174, v64, v65
	v_cvt_pk_bf16_f32 v175, v66, v67
	global_store_dwordx4 v[160:161], v[172:175], off offset:256
	v_mad_i64_i32 v[162:163], vcc, s17, v146, 0
	v_lshl_add_u64 v[160:161], v[162:163], 1, v[156:157]
	v_lshl_add_u64 v[164:165], v[160:161], 0, s[100:101]
	global_load_dwordx4 v[226:229], v[160:161], off
	global_load_dwordx4 v[230:233], v[160:161], off offset:256
	global_load_dwordx4 v[234:237], v[164:165], off
	global_load_dwordx4 v[246:249], v[164:165], off offset:256
	s_waitcnt vmcnt(6)
	v_lshlrev_b32_e32 v164, 16, v210
	v_and_b32_e32 v165, 0xffff0000, v210
	v_lshlrev_b32_e32 v166, 16, v218
	v_and_b32_e32 v167, 0xffff0000, v218
	v_lshlrev_b32_e32 v168, 16, v211
	v_and_b32_e32 v169, 0xffff0000, v211
	v_lshlrev_b32_e32 v170, 16, v219
	v_and_b32_e32 v171, 0xffff0000, v219
	v_pk_fma_f32 v[164:165], v[178:179], v[166:167], v[164:165]
	v_pk_fma_f32 v[168:169], v[180:181], v[170:171], v[168:169]
	v_pk_fma_f32 v[60:61], v[194:195], v[60:61], v[164:165]
	v_pk_fma_f32 v[62:63], v[196:197], v[62:63], v[168:169]
	v_lshlrev_b32_e32 v164, 16, v212
	v_and_b32_e32 v165, 0xffff0000, v212
	v_lshlrev_b32_e32 v166, 16, v220
	v_and_b32_e32 v167, 0xffff0000, v220
	v_lshlrev_b32_e32 v168, 16, v213
	v_and_b32_e32 v169, 0xffff0000, v213
	v_lshlrev_b32_e32 v170, 16, v221
	v_and_b32_e32 v171, 0xffff0000, v221
	v_pk_fma_f32 v[164:165], v[182:183], v[166:167], v[164:165]
	v_pk_fma_f32 v[168:169], v[184:185], v[170:171], v[168:169]
	v_pk_fma_f32 v[56:57], v[198:199], v[56:57], v[164:165]
	v_pk_fma_f32 v[58:59], v[200:201], v[58:59], v[168:169]
	s_nop 0
	v_cvt_pk_bf16_f32 v172, v60, v61
	v_cvt_pk_bf16_f32 v173, v62, v63
	v_cvt_pk_bf16_f32 v174, v56, v57
	v_cvt_pk_bf16_f32 v175, v58, v59
	global_store_dwordx4 v[158:159], v[172:175], off
	v_lshlrev_b32_e32 v164, 16, v214
	v_and_b32_e32 v165, 0xffff0000, v214
	v_lshlrev_b32_e32 v166, 16, v222
	v_and_b32_e32 v167, 0xffff0000, v222
	v_lshlrev_b32_e32 v168, 16, v215
	v_and_b32_e32 v169, 0xffff0000, v215
	v_lshlrev_b32_e32 v170, 16, v223
	v_and_b32_e32 v171, 0xffff0000, v223
	v_pk_fma_f32 v[164:165], v[186:187], v[166:167], v[164:165]
	v_pk_fma_f32 v[168:169], v[188:189], v[170:171], v[168:169]
	v_pk_fma_f32 v[44:45], v[202:203], v[44:45], v[164:165]
	v_pk_fma_f32 v[46:47], v[204:205], v[46:47], v[168:169]
	v_lshlrev_b32_e32 v164, 16, v216
	v_and_b32_e32 v165, 0xffff0000, v216
	v_lshlrev_b32_e32 v166, 16, v224
	v_and_b32_e32 v167, 0xffff0000, v224
	v_lshlrev_b32_e32 v168, 16, v217
	v_and_b32_e32 v169, 0xffff0000, v217
	v_lshlrev_b32_e32 v170, 16, v225
	v_and_b32_e32 v171, 0xffff0000, v225
	v_pk_fma_f32 v[164:165], v[190:191], v[166:167], v[164:165]
	v_pk_fma_f32 v[168:169], v[192:193], v[170:171], v[168:169]
	v_pk_fma_f32 v[40:41], v[206:207], v[40:41], v[164:165]
	v_pk_fma_f32 v[42:43], v[208:209], v[42:43], v[168:169]
	s_nop 0
	v_cvt_pk_bf16_f32 v172, v44, v45
	v_cvt_pk_bf16_f32 v173, v46, v47
	v_cvt_pk_bf16_f32 v174, v40, v41
	v_cvt_pk_bf16_f32 v175, v42, v43
	global_store_dwordx4 v[158:159], v[172:175], off offset:256
	v_mad_i64_i32 v[162:163], vcc, s17, v148, 0
	v_lshl_add_u64 v[158:159], v[162:163], 1, v[156:157]
	v_lshl_add_u64 v[164:165], v[158:159], 0, s[100:101]
	global_load_dwordx4 v[210:213], v[158:159], off
	global_load_dwordx4 v[214:217], v[158:159], off offset:256
	global_load_dwordx4 v[218:221], v[164:165], off
	global_load_dwordx4 v[222:225], v[164:165], off offset:256
	s_waitcnt vmcnt(6)
; #define LAS __attribute__((address_space(3)))
; __device__ __forceinline__ unsigned cvt_pk_bf16(float lo, float hi) { const f32x2 v = {lo, hi}; return __builtin_bit_cast(unsigned, __builtin_convertvector(v, bf16x2_t)); }
; __device__ __forceinline__ float bf_lo(unsigned u) { return __uint_as_float(u << 16); }
; __device__ __forceinline__ float bf_hi(unsigned u) { return __uint_as_float(u & 0xffff0000u); }
;     template <class Sched> __device__ __forceinline__ void operator()(const f32x4 (&acc)[2][2][4][2], const Unit& u, const Sched& S, int wr, int wc, int fr, int fq) const {
;     ...
;                 for (int m = 0; m < 4; ++m) { bf16_t* rowp = base + (size_t)(rl0 + ai * HALF + m * 16) * ldo + cl0;
; #pragma unroll
;                     for (int bj = 0; bj < 2; ++bj) { const f32x4 v0 = acc[ai][bj][m][0], v1 = acc[ai][bj][m][1];
;                         u32x4 w; w.x = cvt_pk_bf16(v0[0], v0[1]); w.y = cvt_pk_bf16(v0[2], v0[3]); w.z = cvt_pk_bf16(v1[0], v1[1]); w.w = cvt_pk_bf16(v1[2], v1[3]);
;                         *(u32x4*)(rowp + bj * HALF) = w; } }
; __device__ __forceinline__ void norm_mod_phase(Frame& F, int L, const float* gvec, int sh_chunk, int nrows, const float* pg, const float* pg2, const float* xlat, const float* xctx) {
;     ...
;         if (h2) {
;             const LAS f32x4* gq = vq + 3 * (D / 4); u32x2* xw_ = (u32x2*)((bf16_t*)(F.ws + WS_XB) + (size_t)r * D) + lane;
; #pragma unroll
;             for (int j = 0; j < 8; ++j) { const u32x2 yy = aux[1][j]; const f32x4 y4 = {bf_lo(yy.x), bf_hi(yy.x), bf_lo(yy.y), bf_hi(yy.y)}; v[j] += gq[64 * j] * y4; u32x2 w; w.x = cvt_pk_bf16(v[j].x, v[j].y); w.y = cvt_pk_bf16(v[j].z, v[j].w); xw_[64 * j] = w; }
;         }
	v_lshlrev_b32_e32 v164, 16, v226
	v_and_b32_e32 v165, 0xffff0000, v226
	v_lshlrev_b32_e32 v166, 16, v234
	v_and_b32_e32 v167, 0xffff0000, v234
	v_lshlrev_b32_e32 v168, 16, v227
	v_and_b32_e32 v169, 0xffff0000, v227
	v_lshlrev_b32_e32 v170, 16, v235
	v_and_b32_e32 v171, 0xffff0000, v235
	v_pk_fma_f32 v[164:165], v[178:179], v[166:167], v[164:165]
	v_pk_fma_f32 v[168:169], v[180:181], v[170:171], v[168:169]
	v_pk_fma_f32 v[52:53], v[194:195], v[52:53], v[164:165]
	v_pk_fma_f32 v[54:55], v[196:197], v[54:55], v[168:169]
	v_lshlrev_b32_e32 v164, 16, v228
	v_and_b32_e32 v165, 0xffff0000, v228
	v_lshlrev_b32_e32 v166, 16, v236
	v_and_b32_e32 v167, 0xffff0000, v236
	v_lshlrev_b32_e32 v168, 16, v229
	v_and_b32_e32 v169, 0xffff0000, v229
	v_lshlrev_b32_e32 v170, 16, v237
	v_and_b32_e32 v171, 0xffff0000, v237
	v_pk_fma_f32 v[164:165], v[182:183], v[166:167], v[164:165]
	v_pk_fma_f32 v[168:169], v[184:185], v[170:171], v[168:169]
	v_pk_fma_f32 v[48:49], v[198:199], v[48:49], v[164:165]
	v_pk_fma_f32 v[50:51], v[200:201], v[50:51], v[168:169]
	s_nop 0
	v_cvt_pk_bf16_f32 v172, v52, v53
	v_cvt_pk_bf16_f32 v173, v54, v55
	v_cvt_pk_bf16_f32 v174, v48, v49
	v_cvt_pk_bf16_f32 v175, v50, v51
	global_store_dwordx4 v[160:161], v[172:175], off
	v_lshlrev_b32_e32 v164, 16, v230
	v_and_b32_e32 v165, 0xffff0000, v230
	v_lshlrev_b32_e32 v166, 16, v246
	v_and_b32_e32 v167, 0xffff0000, v246
	v_lshlrev_b32_e32 v168, 16, v231
	v_and_b32_e32 v169, 0xffff0000, v231
	v_lshlrev_b32_e32 v170, 16, v247
	v_and_b32_e32 v171, 0xffff0000, v247
	v_pk_fma_f32 v[164:165], v[186:187], v[166:167], v[164:165]
	v_pk_fma_f32 v[168:169], v[188:189], v[170:171], v[168:169]
	v_pk_fma_f32 v[28:29], v[202:203], v[28:29], v[164:165]
	v_pk_fma_f32 v[30:31], v[204:205], v[30:31], v[168:169]
	v_lshlrev_b32_e32 v164, 16, v232
	v_and_b32_e32 v165, 0xffff0000, v232
	v_lshlrev_b32_e32 v166, 16, v248
	v_and_b32_e32 v167, 0xffff0000, v248
	v_lshlrev_b32_e32 v168, 16, v233
	v_and_b32_e32 v169, 0xffff0000, v233
	v_lshlrev_b32_e32 v170, 16, v249
	v_and_b32_e32 v171, 0xffff0000, v249
	v_pk_fma_f32 v[164:165], v[190:191], v[166:167], v[164:165]
	v_pk_fma_f32 v[168:169], v[192:193], v[170:171], v[168:169]
	v_pk_fma_f32 v[24:25], v[206:207], v[24:25], v[164:165]
	v_pk_fma_f32 v[26:27], v[208:209], v[26:27], v[168:169]
	s_nop 0
	v_cvt_pk_bf16_f32 v172, v28, v29
	v_cvt_pk_bf16_f32 v173, v30, v31
	v_cvt_pk_bf16_f32 v174, v24, v25
	v_cvt_pk_bf16_f32 v175, v26, v27
	global_store_dwordx4 v[160:161], v[172:175], off offset:256
	v_mad_i64_i32 v[162:163], vcc, s17, v150, 0
	v_lshl_add_u64 v[160:161], v[162:163], 1, v[156:157]
	v_lshl_add_u64 v[164:165], v[160:161], 0, s[100:101]
	global_load_dwordx4 v[226:229], v[160:161], off
	global_load_dwordx4 v[230:233], v[160:161], off offset:256
	global_load_dwordx4 v[234:237], v[164:165], off
	global_load_dwordx4 v[246:249], v[164:165], off offset:256
	s_waitcnt vmcnt(6)
; __device__ __forceinline__ unsigned cvt_pk_bf16(float lo, float hi) { const f32x2 v = {lo, hi}; return __builtin_bit_cast(unsigned, __builtin_convertvector(v, bf16x2_t)); }
;     __device__ __forceinline__ const char* a(const pg8::Unit& u) const { return (const char*)ws + aoff + (size_t)u.pm * 256 * K_ * 2 + (u.kq < 0 ? 0 : u.kq * (K_ / 4) * 2); }
;     __device__ __forceinline__ const char* b(const pg8::Unit& u) const { return (const char*)ws + boff + (size_t)u.pn * 256 * K_ * 2 + (u.kq < 0 ? 0 : u.kq * (K_ / 4) * 2); }
;     __device__ __forceinline__ const char* a(const pg8::Unit& u) const { return (const char*)ws + WS_A + (size_t)u.pm * 256 * D * 2; }
;     __device__ __forceinline__ const char* b(const pg8::Unit& u) const { return (const char*)ws + boff + (size_t)u.pn * 256 * D * 2; }
;     __device__ __forceinline__ const char* a(const pg8::Unit& u) const { return (const char*)ws + WS_A + (size_t)u.pm * 256 * D * 2; }
;     __device__ __forceinline__ const char* b(const pg8::Unit& u) const { return (const char*)ws + boff + (size_t)u.pn * 256 * D * 2; }
;     template <class Sched> __device__ __forceinline__ void operator()(const f32x4 (&acc)[2][2][4][2], const Unit& u, const Sched& S, int wr, int wc, int fr, int fq) const {
;     ...
;                 for (int m = 0; m < 4; ++m) { bf16_t* rowp = base + (size_t)(rl0 + ai * HALF + m * 16) * ldo + cl0;
; #pragma unroll
;                     for (int bj = 0; bj < 2; ++bj) { const f32x4 v0 = acc[ai][bj][m][0], v1 = acc[ai][bj][m][1];
;                         u32x4 w; w.x = cvt_pk_bf16(v0[0], v0[1]); w.y = cvt_pk_bf16(v0[2], v0[3]); w.z = cvt_pk_bf16(v1[0], v1[1]); w.w = cvt_pk_bf16(v1[2], v1[3]);
;                         *(u32x4*)(rowp + bj * HALF) = w; } }
; template <class Epi, class Sched, bool ALIGN_EPI>
; __device__ __forceinline__ void gemm_phase(LAS unsigned char* lds, const int wid, const int lda_, const int ldb_, const int K_, const Sched& S, const Epi& E) {
;     ...
;         if (!has_next) break;
; #pragma unroll
;         for (int a = 0; a < 2; ++a)
; #pragma unroll
;             for (int b = 0; b < 2; ++b)
; #pragma unroll
;                 for (int m = 0; m < 4; ++m)
; #pragma unroll
;                     for (int n = 0; n < 2; ++n) acc[a][b][m][n] = (f32x4){0.f, 0.f, 0.f, 0.f};
;         cur = nxt; cA = nA; cB = nB; ++ui;
	v_lshlrev_b32_e32 v164, 16, v210
	v_and_b32_e32 v165, 0xffff0000, v210
	v_lshlrev_b32_e32 v166, 16, v218
	v_and_b32_e32 v167, 0xffff0000, v218
	v_lshlrev_b32_e32 v168, 16, v211
	v_and_b32_e32 v169, 0xffff0000, v211
	v_lshlrev_b32_e32 v170, 16, v219
	v_and_b32_e32 v171, 0xffff0000, v219
	v_pk_fma_f32 v[164:165], v[178:179], v[166:167], v[164:165]
	v_pk_fma_f32 v[168:169], v[180:181], v[170:171], v[168:169]
	v_pk_fma_f32 v[36:37], v[194:195], v[36:37], v[164:165]
	v_pk_fma_f32 v[38:39], v[196:197], v[38:39], v[168:169]
	v_lshlrev_b32_e32 v164, 16, v212
	v_and_b32_e32 v165, 0xffff0000, v212
	v_lshlrev_b32_e32 v166, 16, v220
	v_and_b32_e32 v167, 0xffff0000, v220
	v_lshlrev_b32_e32 v168, 16, v213
	v_and_b32_e32 v169, 0xffff0000, v213
	v_lshlrev_b32_e32 v170, 16, v221
	v_and_b32_e32 v171, 0xffff0000, v221
	v_pk_fma_f32 v[164:165], v[182:183], v[166:167], v[164:165]
	v_pk_fma_f32 v[168:169], v[184:185], v[170:171], v[168:169]
	v_pk_fma_f32 v[32:33], v[198:199], v[32:33], v[164:165]
	v_pk_fma_f32 v[34:35], v[200:201], v[34:35], v[168:169]
	s_nop 0
	v_cvt_pk_bf16_f32 v172, v36, v37
	v_cvt_pk_bf16_f32 v173, v38, v39
	v_cvt_pk_bf16_f32 v174, v32, v33
	v_cvt_pk_bf16_f32 v175, v34, v35
	global_store_dwordx4 v[158:159], v[172:175], off
	v_lshlrev_b32_e32 v164, 16, v214
	v_and_b32_e32 v165, 0xffff0000, v214
	v_lshlrev_b32_e32 v166, 16, v222
	v_and_b32_e32 v167, 0xffff0000, v222
	v_lshlrev_b32_e32 v168, 16, v215
	v_and_b32_e32 v169, 0xffff0000, v215
	v_lshlrev_b32_e32 v170, 16, v223
	v_and_b32_e32 v171, 0xffff0000, v223
	v_pk_fma_f32 v[164:165], v[186:187], v[166:167], v[164:165]
	v_pk_fma_f32 v[168:169], v[188:189], v[170:171], v[168:169]
	v_pk_fma_f32 v[12:13], v[202:203], v[12:13], v[164:165]
	v_pk_fma_f32 v[14:15], v[204:205], v[14:15], v[168:169]
	v_lshlrev_b32_e32 v164, 16, v216
	v_and_b32_e32 v165, 0xffff0000, v216
	v_lshlrev_b32_e32 v166, 16, v224
	v_and_b32_e32 v167, 0xffff0000, v224
	v_lshlrev_b32_e32 v168, 16, v217
	v_and_b32_e32 v169, 0xffff0000, v217
	v_lshlrev_b32_e32 v170, 16, v225
	v_and_b32_e32 v171, 0xffff0000, v225
	v_pk_fma_f32 v[164:165], v[190:191], v[166:167], v[164:165]
	v_pk_fma_f32 v[168:169], v[192:193], v[170:171], v[168:169]
	v_pk_fma_f32 v[8:9], v[206:207], v[8:9], v[164:165]
	v_pk_fma_f32 v[10:11], v[208:209], v[10:11], v[168:169]
	s_nop 0
	v_cvt_pk_bf16_f32 v172, v12, v13
	v_cvt_pk_bf16_f32 v173, v14, v15
	v_cvt_pk_bf16_f32 v174, v8, v9
	v_cvt_pk_bf16_f32 v175, v10, v11
	global_store_dwordx4 v[158:159], v[172:175], off offset:256
	s_waitcnt vmcnt(2)
	v_lshlrev_b32_e32 v164, 16, v226
	v_and_b32_e32 v165, 0xffff0000, v226
	v_lshlrev_b32_e32 v166, 16, v234
	v_and_b32_e32 v167, 0xffff0000, v234
	v_lshlrev_b32_e32 v168, 16, v227
	v_and_b32_e32 v169, 0xffff0000, v227
	v_lshlrev_b32_e32 v170, 16, v235
	v_and_b32_e32 v171, 0xffff0000, v235
	v_pk_fma_f32 v[164:165], v[178:179], v[166:167], v[164:165]
	v_pk_fma_f32 v[168:169], v[180:181], v[170:171], v[168:169]
	v_pk_fma_f32 v[20:21], v[194:195], v[20:21], v[164:165]
	v_pk_fma_f32 v[22:23], v[196:197], v[22:23], v[168:169]
	v_lshlrev_b32_e32 v164, 16, v228
	v_and_b32_e32 v165, 0xffff0000, v228
	v_lshlrev_b32_e32 v166, 16, v236
	v_and_b32_e32 v167, 0xffff0000, v236
	v_lshlrev_b32_e32 v168, 16, v229
	v_and_b32_e32 v169, 0xffff0000, v229
	v_lshlrev_b32_e32 v170, 16, v237
	v_and_b32_e32 v171, 0xffff0000, v237
	v_pk_fma_f32 v[164:165], v[182:183], v[166:167], v[164:165]
	v_pk_fma_f32 v[168:169], v[184:185], v[170:171], v[168:169]
	v_pk_fma_f32 v[16:17], v[198:199], v[16:17], v[164:165]
	v_pk_fma_f32 v[18:19], v[200:201], v[18:19], v[168:169]
	s_nop 0
	v_cvt_pk_bf16_f32 v172, v20, v21
	v_cvt_pk_bf16_f32 v173, v22, v23
	v_cvt_pk_bf16_f32 v174, v16, v17
	v_cvt_pk_bf16_f32 v175, v18, v19
	global_store_dwordx4 v[160:161], v[172:175], off
	v_lshlrev_b32_e32 v164, 16, v230
	v_and_b32_e32 v165, 0xffff0000, v230
	v_lshlrev_b32_e32 v166, 16, v246
	v_and_b32_e32 v167, 0xffff0000, v246
	v_lshlrev_b32_e32 v168, 16, v231
	v_and_b32_e32 v169, 0xffff0000, v231
	v_lshlrev_b32_e32 v170, 16, v247
	v_and_b32_e32 v171, 0xffff0000, v247
	v_pk_fma_f32 v[164:165], v[186:187], v[166:167], v[164:165]
	v_pk_fma_f32 v[168:169], v[188:189], v[170:171], v[168:169]
	v_pk_fma_f32 v[4:5], v[202:203], v[4:5], v[164:165]
	v_pk_fma_f32 v[6:7], v[204:205], v[6:7], v[168:169]
	v_lshlrev_b32_e32 v164, 16, v232
	v_and_b32_e32 v165, 0xffff0000, v232
	v_lshlrev_b32_e32 v166, 16, v248
	v_and_b32_e32 v167, 0xffff0000, v248
	v_lshlrev_b32_e32 v168, 16, v233
	v_and_b32_e32 v169, 0xffff0000, v233
	v_lshlrev_b32_e32 v170, 16, v249
	v_and_b32_e32 v171, 0xffff0000, v249
	v_pk_fma_f32 v[164:165], v[190:191], v[166:167], v[164:165]
	v_pk_fma_f32 v[168:169], v[192:193], v[170:171], v[168:169]
	v_pk_fma_f32 v[0:1], v[206:207], v[0:1], v[164:165]
	v_pk_fma_f32 v[2:3], v[208:209], v[2:3], v[168:169]
	s_nop 0
	v_cvt_pk_bf16_f32 v172, v4, v5
	v_cvt_pk_bf16_f32 v173, v6, v7
	v_cvt_pk_bf16_f32 v174, v0, v1
	v_cvt_pk_bf16_f32 v175, v2, v3
	global_store_dwordx4 v[160:161], v[172:175], off offset:256
	s_and_b64 vcc, exec, s[40:41]
	s_mov_b32 s38, s75
	s_mov_b32 s34, s73
	s_mov_b32 s30, s74
	s_mov_b64 s[48:49], s[36:37]
	s_mov_b64 s[46:47], s[42:43]
	s_cbranch_vccnz .LBB0_1346
	s_branch .LBB0_1327
